# last-layer out-proj epilogue: dropped the per-workgroup L2 writeback before the panel counter (only atomics are exchanged there)
# speedup vs baseline: 1.0423x; 1.0175x over previous
.LBB0_806:
	s_or_b64 exec, exec, s[34:35]
	s_waitcnt vmcnt(0)
	v_readlane_b32 s2, v253, 0
	v_readlane_b32 s3, v253, 1
	s_waitcnt lgkmcnt(0)
	s_barrier
	s_and_saveexec_b64 s[34:35], s[2:3]
	s_cbranch_execz .LBB0_818
	s_lshl_b32 s20, s44, 6
	s_ashr_i32 s21, s20, 31
	s_lshl_b64 s[20:21], s[20:21], 2
	s_mov_b64 s[42:43], exec
	s_waitcnt vmcnt(0)
	s_waitcnt vmcnt(0)
	s_getpc_b64 s[36:37]
	s_add_u32 s36, s36, g_ctl@rel32@lo+32772
	s_addc_u32 s37, s37, g_ctl@rel32@hi+32780
	v_mbcnt_lo_u32_b32 v152, s42, 0
	s_add_u32 s36, s36, s20
	v_mbcnt_hi_u32_b32 v152, s43, v152
	s_addc_u32 s37, s37, s21
	v_cmp_eq_u32_e32 vcc, 0, v152
	s_and_saveexec_b64 s[44:45], vcc
	s_cbranch_execz .LBB0_809
	s_bcnt1_i32_b64 s2, s[42:43]
	v_mov_b32_e32 v152, s2
	global_atomic_add v191, v152, s[36:37]
